# attention main loop specialised per wave group (waves 0-3 / 4-7): no run-time role tests or taken branches around the third K chunk and the group barriers
# speedup vs baseline: 1.0109x; 1.0109x over previous
; #define SLOAD(i, k0) do { sr_[i].vs = *(const u32x4*)(vsrc + (k0)); \
;     { const unsigned char* kt_ = Kh + (size_t)(k0) * 192; sr_[i].ks0 = *(const u32x4*)(kt_ + tid * 16); if (k2) sr_[i].ks1 = *(const u32x4*)(kt_ + 8192 + tid * 16); } } while (0)
; __device__ __forceinline__ void attn_body(const unsigned char* __restrict__ Qb, const unsigned char* __restrict__ Kh, const unsigned char* __restrict__ Vt,
;                                           bf16_t* __restrict__ Ob, int seq, char* lds) {
;     ...
;   int sP = 0, sC = 1, sN = 2;
;   SLOAD(0, 0); asm volatile("s_waitcnt vmcnt(0)" ::: "memory"); SWRITE(0, 0); SLOAD(0, KVBLK); __syncthreads();
;   asm volatile("s_waitcnt vmcnt(0)" ::: "memory"); SWRITE(1, 0); if (2 < NT) SLOAD(0, 2 * KVBLK);
;   qkt(pA0, pA1, K_lds, qr, r32, hi); partialSM(pA0, pA1, m_reg, mnA, alA);
;   for (int j = 1; j + 1 < NT; j += 2) {
;     STEP(j, pB0, pB1, mnB, alB, pA0, pA1, alA);
;     STEP(j + 1, pA0, pA1, mnA, alA, pB0, pB1, alB);
;   }
.Latt_p5:
	v_mov_b32_e32 v202, v140
	v_mov_b32_e32 v203, v141
	v_mov_b32_e32 v204, v142
	v_mov_b32_e32 v205, v143
	v_mov_b32_e32 v206, v144
	v_mov_b32_e32 v207, v145
	v_mov_b32_e32 v208, v146
	v_mov_b32_e32 v209, v147
	v_mov_b32_e32 v210, v148
	v_mov_b32_e32 v211, v149
	v_mov_b32_e32 v212, v150
	v_mov_b32_e32 v213, v151
	s_waitcnt lgkmcnt(0)
	s_barrier
	ds_read_b128 v[128:131], v220 offset:0
	ds_read_b128 v[132:135], v220 offset:16
	ds_read_b128 v[136:139], v220 offset:6656
	ds_read_b128 v[140:143], v220 offset:6672
	ds_read_b128 v[144:147], v220 offset:64
	ds_read_b128 v[148:151], v220 offset:80
	ds_read_b128 v[152:155], v220 offset:6720
	ds_read_b128 v[156:159], v220 offset:6736
	s_mov_b32 s6, 0
	s_cmp_eq_u32 s7, 0
	s_cbranch_scc0 .Latt_loop_r1
.Latt_loop_r0:
	s_cmp_eq_u32 s6, 0
	s_cbranch_scc1 .Latt_m_first_r0
	s_add_u32 s4, s6, 2
	ds_read_b128 v[176:179], v221 offset:30720
	ds_read_b128 v[180:183], v221 offset:30736
	ds_read_b128 v[184:187], v221 offset:33280
	ds_read_b128 v[188:191], v221 offset:33296
	s_waitcnt lgkmcnt(4)
	v_mfma_scale_f32_32x32x64_f8f6f4 v[64:79], v[128:135], v[96:103], v[160:175], v235, v201 op_sel_hi:[0,0,0]
	ds_read_b128 v[128:131], v220 offset:128
	ds_read_b128 v[132:135], v220 offset:144
	v_mfma_scale_f32_32x32x64_f8f6f4 v[80:95], v[136:143], v[96:103], v[160:175], v235, v201 op_sel_hi:[0,0,0]
	ds_read_b128 v[136:139], v220 offset:6784
	ds_read_b128 v[140:143], v220 offset:6800
	s_cmp_lt_u32 s4, 128
	s_cbranch_scc0 .Latt_ms0_r0_nowr
	s_waitcnt vmcnt(0)
	ds_write2_b32 v225, v202, v204 offset1:1
	ds_write2_b32 v225, v203, v205 offset0:8 offset1:9
	ds_write_b128 v218, v[206:209] offset:26624
	ds_write_b128 v219, v[210:213] offset:26624
.Latt_ms0_r0_nowr:
	v_mfma_scale_f32_32x32x64_f8f6f4 v[64:79], v[144:151], v[104:111], v[64:79], v235, v201 op_sel_hi:[0,0,0]
	ds_read_b128 v[144:147], v220 offset:13376
	ds_read_b128 v[148:151], v220 offset:13392
	v_mfma_scale_f32_32x32x64_f8f6f4 v[80:95], v[152:159], v[104:111], v[80:95], v235, v201 op_sel_hi:[0,0,0]
	ds_read_b128 v[152:155], v220 offset:20032
	ds_read_b128 v[156:159], v220 offset:20048
	s_cmp_lt_u32 s4, 127
	s_cbranch_scc0 .Latt_ms0_r0_nold
	global_load_dwordx4 v[202:205], v216, s[10:11]
	global_load_dwordx4 v[206:209], v214, s[8:9]
	global_load_dwordx4 v[210:213], v215, s[8:9]
	s_add_u32 s8, s8, 0x3000
	s_addc_u32 s9, s9, 0
	s_add_u32 s10, s10, 64
	s_addc_u32 s11, s11, 0

; __device__ __forceinline__ void attn_body(const unsigned char* __restrict__ Qb, const unsigned char* __restrict__ Kh, const unsigned char* __restrict__ Vt,
;                                           bf16_t* __restrict__ Ob, int seq, char* lds) {
;     ...
;   f32x16 pA0, pA1, pB0, pB1; float mnA, mnB, alA, alB; i32x8 pa; const int NT = seq / KVBLK;
.Latt_m_first_r0:
	s_add_u32 s4, s6, 2
	s_waitcnt lgkmcnt(0)
	v_mfma_scale_f32_32x32x64_f8f6f4 v[64:79], v[128:135], v[96:103], v[160:175], v235, v201 op_sel_hi:[0,0,0]
	ds_read_b128 v[128:131], v220 offset:128
	ds_read_b128 v[132:135], v220 offset:144
	v_mfma_scale_f32_32x32x64_f8f6f4 v[80:95], v[136:143], v[96:103], v[160:175], v235, v201 op_sel_hi:[0,0,0]
	ds_read_b128 v[136:139], v220 offset:6784
	ds_read_b128 v[140:143], v220 offset:6800
	s_cmp_lt_u32 s4, 128
	s_cbranch_scc0 .Latt_mf_r0_nowr
	s_waitcnt vmcnt(0)
	ds_write2_b32 v225, v202, v204 offset1:1
	ds_write2_b32 v225, v203, v205 offset0:8 offset1:9
	ds_write_b128 v218, v[206:209] offset:26624
	ds_write_b128 v219, v[210:213] offset:26624

; __device__ __forceinline__ void partialSM(f32x16& p0, f32x16& p1, float& m_reg, float& mn, float& alpha) {
;   constexpr float C = SCALE * 1.4426950408889634f;
;   float pmax = p0[0]; for (int r = 1; r < 16; ++r) pmax = fmaxf(pmax, p0[r]); for (int r = 0; r < 16; ++r) pmax = fmaxf(pmax, p1[r]);
;   { auto rr = __builtin_amdgcn_permlane32_swap(__float_as_uint(pmax), __float_as_uint(pmax), false, false);
;     pmax = fmaxf(__uint_as_float(rr[0]), __uint_as_float(rr[1])); }
;   if (__builtin_expect(__all(pmax - m_reg <= THR / SCALE), 1)) { mn = m_reg; alpha = 1.f; }
;   else { mn = fmaxf(m_reg, pmax); alpha = __builtin_amdgcn_exp2f((m_reg - mn) * C); m_reg = mn; }
;   float mnC = -mn * C + 5.f;
;   for (int r = 0; r < 16; ++r) p0[r] = fmaf(p0[r], C, mnC); for (int r = 0; r < 16; ++r) p1[r] = fmaf(p1[r], C, mnC);
;   for (int r = 0; r < 16; ++r) p0[r] = __builtin_amdgcn_exp2f(p0[r]);
; }
; __device__ __forceinline__ void finishSM(f32x16& p0, f32x16& p1, float alpha, float& l_reg, i32x8& pa) {
;   for (int r = 0; r < 16; ++r) p1[r] = __builtin_amdgcn_exp2f(p1[r]);
;   float ps = 0; for (int r = 0; r < 16; ++r) ps += p0[r]; for (int r = 0; r < 16; ++r) ps += p1[r];
;   { auto rr = __builtin_amdgcn_permlane32_swap(__float_as_uint(ps), __float_as_uint(ps), false, false);
;     ps = __uint_as_float(rr[0]) + __uint_as_float(rr[1]); }
;   l_reg = l_reg * alpha + ps;
; #pragma unroll
;   for (int i = 0; i < 4; ++i) { int w0 = 0, w1 = 0;
;     w0 = __builtin_amdgcn_cvt_pk_fp8_f32(p0[4 * i], p0[4 * i + 1], w0, false); w0 = __builtin_amdgcn_cvt_pk_fp8_f32(p0[4 * i + 2], p0[4 * i + 3], w0, true);
;     w1 = __builtin_amdgcn_cvt_pk_fp8_f32(p1[4 * i], p1[4 * i + 1], w1, false); w1 = __builtin_amdgcn_cvt_pk_fp8_f32(p1[4 * i + 2], p1[4 * i + 3], w1, true);
;     pa[i] = w0; pa[4 + i] = w1; }
; }
.Latt_m_done_0_r0:
	s_nop 3
	v_max3_f32 v228, v64, v65, v66
	v_max3_f32 v229, v80, v81, v82
	v_max3_f32 v228, v228, v67, v68
	v_max3_f32 v229, v229, v83, v84
	v_max3_f32 v228, v228, v69, v70
	v_max3_f32 v229, v229, v85, v86
	v_max3_f32 v228, v228, v71, v72
	v_max3_f32 v229, v229, v87, v88
	v_max3_f32 v228, v228, v73, v74
	v_max3_f32 v229, v229, v89, v90
	v_max3_f32 v228, v228, v75, v76
	v_max3_f32 v229, v229, v91, v92
	v_max3_f32 v228, v228, v77, v78
	v_max3_f32 v229, v229, v93, v94
	v_max3_f32 v228, v228, v79, v95
	v_max_f32_e32 v228, v228, v229
	s_mov_b32 s5, 0
	v_cmp_ge_f32_e32 vcc, s13, v228
	v_mov_b32_e32 v226, 1.0
	s_cmp_eq_u32 s6, 0
	s_cbranch_scc1 .Latt_rare
	s_cmp_eq_u64 vcc, exec
	s_cbranch_scc0 .Latt_rare
.Latt_rare_back_0:
	v_exp_f32_e32 v64, v64
	v_exp_f32_e32 v65, v65
	v_exp_f32_e32 v66, v66
	v_exp_f32_e32 v67, v67
	v_add_f32_e32 v230, v64, v65
	v_exp_f32_e32 v68, v68
	v_add_f32_e32 v230, v66, v230
	v_exp_f32_e32 v69, v69
	v_cvt_pk_fp8_f32 v120, v64, v65
	v_add_f32_e32 v230, v67, v230
	v_exp_f32_e32 v70, v70
	v_add_f32_e32 v230, v68, v230
	v_exp_f32_e32 v71, v71
	v_cvt_pk_fp8_f32 v120, v66, v67 op_sel:[0,0,1]
	v_add_f32_e32 v230, v69, v230
	v_exp_f32_e32 v72, v72
	v_add_f32_e32 v230, v70, v230
	v_exp_f32_e32 v73, v73
	v_cvt_pk_fp8_f32 v121, v68, v69
	v_add_f32_e32 v230, v71, v230
	v_exp_f32_e32 v74, v74
	v_add_f32_e32 v230, v72, v230
	v_exp_f32_e32 v75, v75
	v_cvt_pk_fp8_f32 v121, v70, v71 op_sel:[0,0,1]
	v_add_f32_e32 v230, v73, v230
	v_exp_f32_e32 v76, v76
	v_add_f32_e32 v230, v74, v230
	v_exp_f32_e32 v77, v77
	v_cvt_pk_fp8_f32 v122, v72, v73
	v_add_f32_e32 v230, v75, v230
	v_exp_f32_e32 v78, v78
	v_add_f32_e32 v230, v76, v230
	v_exp_f32_e32 v79, v79
	v_cvt_pk_fp8_f32 v122, v74, v75 op_sel:[0,0,1]
	v_add_f32_e32 v230, v77, v230
	v_exp_f32_e32 v80, v80
	v_add_f32_e32 v230, v78, v230
	v_exp_f32_e32 v81, v81
	v_cvt_pk_fp8_f32 v123, v76, v77
	v_add_f32_e32 v230, v79, v230
	v_exp_f32_e32 v82, v82
	v_add_f32_e32 v230, v80, v230
	v_exp_f32_e32 v83, v83
	v_cvt_pk_fp8_f32 v123, v78, v79 op_sel:[0,0,1]
	v_add_f32_e32 v230, v81, v230
	v_exp_f32_e32 v84, v84
	v_add_f32_e32 v230, v82, v230
	v_exp_f32_e32 v85, v85
	v_cvt_pk_fp8_f32 v124, v80, v81
	v_add_f32_e32 v230, v83, v230
	v_exp_f32_e32 v86, v86
	v_add_f32_e32 v230, v84, v230
	v_exp_f32_e32 v87, v87
	v_cvt_pk_fp8_f32 v124, v82, v83 op_sel:[0,0,1]
	v_add_f32_e32 v230, v85, v230
	v_exp_f32_e32 v88, v88
	v_add_f32_e32 v230, v86, v230
	v_exp_f32_e32 v89, v89
	v_cvt_pk_fp8_f32 v125, v84, v85
	v_add_f32_e32 v230, v87, v230
	v_exp_f32_e32 v90, v90
	v_add_f32_e32 v230, v88, v230
	v_exp_f32_e32 v91, v91
	v_cvt_pk_fp8_f32 v125, v86, v87 op_sel:[0,0,1]
	v_add_f32_e32 v230, v89, v230
	v_exp_f32_e32 v92, v92
	v_add_f32_e32 v230, v90, v230
	v_exp_f32_e32 v93, v93
	v_cvt_pk_fp8_f32 v126, v88, v89
	v_add_f32_e32 v230, v91, v230
	v_exp_f32_e32 v94, v94
	v_add_f32_e32 v230, v92, v230
	v_exp_f32_e32 v95, v95
	v_cvt_pk_fp8_f32 v126, v90, v91 op_sel:[0,0,1]
	v_add_f32_e32 v230, v93, v230
	v_add_f32_e32 v230, v94, v230
	v_cvt_pk_fp8_f32 v127, v92, v93
	v_add_f32_e32 v230, v95, v230
	v_cvt_pk_fp8_f32 v127, v94, v95 op_sel:[0,0,1]
	v_fma_f32 v194, v194, v226, v230
	s_waitcnt lgkmcnt(0)
	s_barrier
	s_add_u32 s6, s6, 1
	s_add_u32 s4, s6, 2
	ds_read_b128 v[176:179], v221 offset:0
	ds_read_b128 v[180:183], v221 offset:16
	ds_read_b128 v[184:187], v221 offset:2560
	ds_read_b128 v[188:191], v221 offset:2576
	s_waitcnt lgkmcnt(4)
	v_mfma_scale_f32_32x32x64_f8f6f4 v[64:79], v[128:135], v[96:103], v[160:175], v235, v201 op_sel_hi:[0,0,0]
	ds_read_b128 v[128:131], v220 offset:13440
	ds_read_b128 v[132:135], v220 offset:13456
	v_mfma_scale_f32_32x32x64_f8f6f4 v[80:95], v[136:143], v[96:103], v[160:175], v235, v201 op_sel_hi:[0,0,0]
	ds_read_b128 v[136:139], v220 offset:20096
	ds_read_b128 v[140:143], v220 offset:20112
	s_cmp_lt_u32 s4, 128
	s_cbranch_scc0 .Latt_ms1_r0_nowr
	v_add_u32_e32 v228, 30720, v217
	s_waitcnt vmcnt(0)
	ds_write2_b32 v228, v202, v204 offset1:1
	ds_write2_b32 v228, v203, v205 offset0:8 offset1:9
	ds_write_b128 v218, v[206:209] offset:39936
	ds_write_b128 v219, v[210:213] offset:39936
.Latt_ms1_r0_nowr:
	v_mfma_scale_f32_32x32x64_f8f6f4 v[64:79], v[144:151], v[104:111], v[64:79], v235, v201 op_sel_hi:[0,0,0]
	ds_read_b128 v[144:147], v220 offset:26688
	ds_read_b128 v[148:151], v220 offset:26704
	v_mfma_scale_f32_32x32x64_f8f6f4 v[80:95], v[152:159], v[104:111], v[80:95], v235, v201 op_sel_hi:[0,0,0]
	ds_read_b128 v[152:155], v220 offset:33344
	ds_read_b128 v[156:159], v220 offset:33360
	s_cmp_lt_u32 s4, 127
	s_cbranch_scc0 .Latt_ms1_r0_nold
	global_load_dwordx4 v[202:205], v216, s[10:11]
	global_load_dwordx4 v[206:209], v214, s[8:9]
	global_load_dwordx4 v[210:213], v215, s[8:9]
	s_add_u32 s8, s8, 0x3000
	s_addc_u32 s9, s9, 0
	s_add_u32 s10, s10, 64
	s_addc_u32 s11, s11, 0

; __device__ __forceinline__ void partialSM(f32x16& p0, f32x16& p1, float& m_reg, float& mn, float& alpha) {
;   constexpr float C = SCALE * 1.4426950408889634f;
;   float pmax = p0[0]; for (int r = 1; r < 16; ++r) pmax = fmaxf(pmax, p0[r]); for (int r = 0; r < 16; ++r) pmax = fmaxf(pmax, p1[r]);
;   { auto rr = __builtin_amdgcn_permlane32_swap(__float_as_uint(pmax), __float_as_uint(pmax), false, false);
;     pmax = fmaxf(__uint_as_float(rr[0]), __uint_as_float(rr[1])); }
;   if (__builtin_expect(__all(pmax - m_reg <= THR / SCALE), 1)) { mn = m_reg; alpha = 1.f; }
;   else { mn = fmaxf(m_reg, pmax); alpha = __builtin_amdgcn_exp2f((m_reg - mn) * C); m_reg = mn; }
;   float mnC = -mn * C + 5.f;
;   for (int r = 0; r < 16; ++r) p0[r] = fmaf(p0[r], C, mnC); for (int r = 0; r < 16; ++r) p1[r] = fmaf(p1[r], C, mnC);
;   for (int r = 0; r < 16; ++r) p0[r] = __builtin_amdgcn_exp2f(p0[r]);
; }
; __device__ __forceinline__ void finishSM(f32x16& p0, f32x16& p1, float alpha, float& l_reg, i32x8& pa) {
;   for (int r = 0; r < 16; ++r) p1[r] = __builtin_amdgcn_exp2f(p1[r]);
;   float ps = 0; for (int r = 0; r < 16; ++r) ps += p0[r]; for (int r = 0; r < 16; ++r) ps += p1[r];
;   { auto rr = __builtin_amdgcn_permlane32_swap(__float_as_uint(ps), __float_as_uint(ps), false, false);
;     ps = __uint_as_float(rr[0]) + __uint_as_float(rr[1]); }
;   l_reg = l_reg * alpha + ps;
; #pragma unroll
;   for (int i = 0; i < 4; ++i) { int w0 = 0, w1 = 0;
;     w0 = __builtin_amdgcn_cvt_pk_fp8_f32(p0[4 * i], p0[4 * i + 1], w0, false); w0 = __builtin_amdgcn_cvt_pk_fp8_f32(p0[4 * i + 2], p0[4 * i + 3], w0, true);
;     w1 = __builtin_amdgcn_cvt_pk_fp8_f32(p1[4 * i], p1[4 * i + 1], w1, false); w1 = __builtin_amdgcn_cvt_pk_fp8_f32(p1[4 * i + 2], p1[4 * i + 3], w1, true);
;     pa[i] = w0; pa[4 + i] = w1; }
; }
.Latt_m_done_1_r0:
	s_nop 3
	v_max3_f32 v228, v64, v65, v66
	v_max3_f32 v229, v80, v81, v82
	v_max3_f32 v228, v228, v67, v68
	v_max3_f32 v229, v229, v83, v84
	v_max3_f32 v228, v228, v69, v70
	v_max3_f32 v229, v229, v85, v86
	v_max3_f32 v228, v228, v71, v72
	v_max3_f32 v229, v229, v87, v88
	v_max3_f32 v228, v228, v73, v74
	v_max3_f32 v229, v229, v89, v90
	v_max3_f32 v228, v228, v75, v76
	v_max3_f32 v229, v229, v91, v92
	v_max3_f32 v228, v228, v77, v78
	v_max3_f32 v229, v229, v93, v94
	v_max3_f32 v228, v228, v79, v95
	v_max_f32_e32 v228, v228, v229
	s_mov_b32 s5, 1
	v_cmp_ge_f32_e32 vcc, s13, v228
	v_mov_b32_e32 v226, 1.0
	s_cmp_eq_u64 vcc, exec
	s_cbranch_scc0 .Latt_rare
.Latt_rare_back_1:
	v_exp_f32_e32 v64, v64
	v_exp_f32_e32 v65, v65
	v_exp_f32_e32 v66, v66
	v_exp_f32_e32 v67, v67
	v_add_f32_e32 v230, v64, v65
	v_exp_f32_e32 v68, v68
	v_add_f32_e32 v230, v66, v230
	v_exp_f32_e32 v69, v69
	v_cvt_pk_fp8_f32 v120, v64, v65
	v_add_f32_e32 v230, v67, v230
	v_exp_f32_e32 v70, v70
	v_add_f32_e32 v230, v68, v230
	v_exp_f32_e32 v71, v71
	v_cvt_pk_fp8_f32 v120, v66, v67 op_sel:[0,0,1]
	v_add_f32_e32 v230, v69, v230
	v_exp_f32_e32 v72, v72
	v_add_f32_e32 v230, v70, v230
	v_exp_f32_e32 v73, v73
	v_cvt_pk_fp8_f32 v121, v68, v69
	v_add_f32_e32 v230, v71, v230
	v_exp_f32_e32 v74, v74
	v_add_f32_e32 v230, v72, v230
	v_exp_f32_e32 v75, v75
	v_cvt_pk_fp8_f32 v121, v70, v71 op_sel:[0,0,1]
	v_add_f32_e32 v230, v73, v230
	v_exp_f32_e32 v76, v76
	v_add_f32_e32 v230, v74, v230
	v_exp_f32_e32 v77, v77
	v_cvt_pk_fp8_f32 v122, v72, v73
	v_add_f32_e32 v230, v75, v230
	v_exp_f32_e32 v78, v78
	v_add_f32_e32 v230, v76, v230
	v_exp_f32_e32 v79, v79
	v_cvt_pk_fp8_f32 v122, v74, v75 op_sel:[0,0,1]
	v_add_f32_e32 v230, v77, v230
	v_exp_f32_e32 v80, v80
	v_add_f32_e32 v230, v78, v230
	v_exp_f32_e32 v81, v81
	v_cvt_pk_fp8_f32 v123, v76, v77
	v_add_f32_e32 v230, v79, v230
	v_exp_f32_e32 v82, v82
	v_add_f32_e32 v230, v80, v230
	v_exp_f32_e32 v83, v83
	v_cvt_pk_fp8_f32 v123, v78, v79 op_sel:[0,0,1]
	v_add_f32_e32 v230, v81, v230
	v_exp_f32_e32 v84, v84
	v_add_f32_e32 v230, v82, v230
	v_exp_f32_e32 v85, v85
	v_cvt_pk_fp8_f32 v124, v80, v81
	v_add_f32_e32 v230, v83, v230
	v_exp_f32_e32 v86, v86
	v_add_f32_e32 v230, v84, v230
	v_exp_f32_e32 v87, v87
	v_cvt_pk_fp8_f32 v124, v82, v83 op_sel:[0,0,1]
	v_add_f32_e32 v230, v85, v230
	v_exp_f32_e32 v88, v88
	v_add_f32_e32 v230, v86, v230
	v_exp_f32_e32 v89, v89
	v_cvt_pk_fp8_f32 v125, v84, v85
	v_add_f32_e32 v230, v87, v230
	v_exp_f32_e32 v90, v90
	v_add_f32_e32 v230, v88, v230
	v_exp_f32_e32 v91, v91
	v_cvt_pk_fp8_f32 v125, v86, v87 op_sel:[0,0,1]
	v_add_f32_e32 v230, v89, v230
	v_exp_f32_e32 v92, v92
	v_add_f32_e32 v230, v90, v230
	v_exp_f32_e32 v93, v93
	v_cvt_pk_fp8_f32 v126, v88, v89
	v_add_f32_e32 v230, v91, v230
	v_exp_f32_e32 v94, v94
	v_add_f32_e32 v230, v92, v230
	v_exp_f32_e32 v95, v95
	v_cvt_pk_fp8_f32 v126, v90, v91 op_sel:[0,0,1]
	v_add_f32_e32 v230, v93, v230
	v_add_f32_e32 v230, v94, v230
	v_cvt_pk_fp8_f32 v127, v92, v93
	v_add_f32_e32 v230, v95, v230
	v_cvt_pk_fp8_f32 v127, v94, v95 op_sel:[0,0,1]
	v_fma_f32 v194, v194, v226, v230
	s_waitcnt lgkmcnt(0)
	s_barrier
	s_add_u32 s6, s6, 1
	s_add_u32 s4, s6, 2
	ds_read_b128 v[176:179], v221 offset:10240
	ds_read_b128 v[180:183], v221 offset:10256
	ds_read_b128 v[184:187], v221 offset:12800
	ds_read_b128 v[188:191], v221 offset:12816
	s_waitcnt lgkmcnt(4)
	v_mfma_scale_f32_32x32x64_f8f6f4 v[64:79], v[128:135], v[96:103], v[160:175], v235, v201 op_sel_hi:[0,0,0]
	ds_read_b128 v[128:131], v220 offset:26752
	ds_read_b128 v[132:135], v220 offset:26768
	v_mfma_scale_f32_32x32x64_f8f6f4 v[80:95], v[136:143], v[96:103], v[160:175], v235, v201 op_sel_hi:[0,0,0]
	ds_read_b128 v[136:139], v220 offset:33408
	ds_read_b128 v[140:143], v220 offset:33424
	s_cmp_lt_u32 s4, 128
	s_cbranch_scc0 .Latt_ms2_r0_nowr
	s_waitcnt vmcnt(0)
	ds_write2_b32 v217, v202, v204 offset1:1
	ds_write2_b32 v217, v203, v205 offset0:8 offset1:9
	ds_write_b128 v218, v[206:209] offset:0
	ds_write_b128 v219, v[210:213] offset:0
.Latt_ms2_r0_nowr:
	v_mfma_scale_f32_32x32x64_f8f6f4 v[64:79], v[144:151], v[104:111], v[64:79], v235, v201 op_sel_hi:[0,0,0]
	ds_read_b128 v[144:147], v220 offset:40000
	ds_read_b128 v[148:151], v220 offset:40016
	v_mfma_scale_f32_32x32x64_f8f6f4 v[80:95], v[152:159], v[104:111], v[80:95], v235, v201 op_sel_hi:[0,0,0]
	ds_read_b128 v[152:155], v220 offset:46656
	ds_read_b128 v[156:159], v220 offset:46672
	s_cmp_lt_u32 s4, 127
	s_cbranch_scc0 .Latt_ms2_r0_nold
	global_load_dwordx4 v[202:205], v216, s[10:11]
	global_load_dwordx4 v[206:209], v214, s[8:9]
	global_load_dwordx4 v[210:213], v215, s[8:9]
	s_add_u32 s8, s8, 0x3000
	s_addc_u32 s9, s9, 0
	s_add_u32 s10, s10, 64
	s_addc_u32 s11, s11, 0

; __device__ __forceinline__ void partialSM(f32x16& p0, f32x16& p1, float& m_reg, float& mn, float& alpha) {
;   constexpr float C = SCALE * 1.4426950408889634f;
;   float pmax = p0[0]; for (int r = 1; r < 16; ++r) pmax = fmaxf(pmax, p0[r]); for (int r = 0; r < 16; ++r) pmax = fmaxf(pmax, p1[r]);
;   { auto rr = __builtin_amdgcn_permlane32_swap(__float_as_uint(pmax), __float_as_uint(pmax), false, false);
;     pmax = fmaxf(__uint_as_float(rr[0]), __uint_as_float(rr[1])); }
;   if (__builtin_expect(__all(pmax - m_reg <= THR / SCALE), 1)) { mn = m_reg; alpha = 1.f; }
;   else { mn = fmaxf(m_reg, pmax); alpha = __builtin_amdgcn_exp2f((m_reg - mn) * C); m_reg = mn; }
;   float mnC = -mn * C + 5.f;
;   for (int r = 0; r < 16; ++r) p0[r] = fmaf(p0[r], C, mnC); for (int r = 0; r < 16; ++r) p1[r] = fmaf(p1[r], C, mnC);
;   for (int r = 0; r < 16; ++r) p0[r] = __builtin_amdgcn_exp2f(p0[r]);
; }
; __device__ __forceinline__ void finishSM(f32x16& p0, f32x16& p1, float alpha, float& l_reg, i32x8& pa) {
;   for (int r = 0; r < 16; ++r) p1[r] = __builtin_amdgcn_exp2f(p1[r]);
;   float ps = 0; for (int r = 0; r < 16; ++r) ps += p0[r]; for (int r = 0; r < 16; ++r) ps += p1[r];
;   { auto rr = __builtin_amdgcn_permlane32_swap(__float_as_uint(ps), __float_as_uint(ps), false, false);
;     ps = __uint_as_float(rr[0]) + __uint_as_float(rr[1]); }
;   l_reg = l_reg * alpha + ps;
; #pragma unroll
;   for (int i = 0; i < 4; ++i) { int w0 = 0, w1 = 0;
;     w0 = __builtin_amdgcn_cvt_pk_fp8_f32(p0[4 * i], p0[4 * i + 1], w0, false); w0 = __builtin_amdgcn_cvt_pk_fp8_f32(p0[4 * i + 2], p0[4 * i + 3], w0, true);
;     w1 = __builtin_amdgcn_cvt_pk_fp8_f32(p1[4 * i], p1[4 * i + 1], w1, false); w1 = __builtin_amdgcn_cvt_pk_fp8_f32(p1[4 * i + 2], p1[4 * i + 3], w1, true);
;     pa[i] = w0; pa[4 + i] = w1; }
; }
.Latt_m_done_2_r0:
	s_nop 3
	v_max3_f32 v228, v64, v65, v66
	v_max3_f32 v229, v80, v81, v82
	v_max3_f32 v228, v228, v67, v68
	v_max3_f32 v229, v229, v83, v84
	v_max3_f32 v228, v228, v69, v70
	v_max3_f32 v229, v229, v85, v86
	v_max3_f32 v228, v228, v71, v72
	v_max3_f32 v229, v229, v87, v88
	v_max3_f32 v228, v228, v73, v74
	v_max3_f32 v229, v229, v89, v90
	v_max3_f32 v228, v228, v75, v76
	v_max3_f32 v229, v229, v91, v92
	v_max3_f32 v228, v228, v77, v78
	v_max3_f32 v229, v229, v93, v94
	v_max3_f32 v228, v228, v79, v95
	v_max_f32_e32 v228, v228, v229
	s_mov_b32 s5, 2
	v_cmp_ge_f32_e32 vcc, s13, v228
	v_mov_b32_e32 v226, 1.0
	s_cmp_eq_u64 vcc, exec
	s_cbranch_scc0 .Latt_rare
.Latt_rare_back_2:
	v_exp_f32_e32 v64, v64
	v_exp_f32_e32 v65, v65
	v_exp_f32_e32 v66, v66
	v_exp_f32_e32 v67, v67
	v_add_f32_e32 v230, v64, v65
	v_exp_f32_e32 v68, v68
	v_add_f32_e32 v230, v66, v230
	v_exp_f32_e32 v69, v69
	v_cvt_pk_fp8_f32 v120, v64, v65
	v_add_f32_e32 v230, v67, v230
	v_exp_f32_e32 v70, v70
	v_add_f32_e32 v230, v68, v230
	v_exp_f32_e32 v71, v71
	v_cvt_pk_fp8_f32 v120, v66, v67 op_sel:[0,0,1]
	v_add_f32_e32 v230, v69, v230
	v_exp_f32_e32 v72, v72
	v_add_f32_e32 v230, v70, v230
	v_exp_f32_e32 v73, v73
	v_cvt_pk_fp8_f32 v121, v68, v69
	v_add_f32_e32 v230, v71, v230
	v_exp_f32_e32 v74, v74
	v_add_f32_e32 v230, v72, v230
	v_exp_f32_e32 v75, v75
	v_cvt_pk_fp8_f32 v121, v70, v71 op_sel:[0,0,1]
	v_add_f32_e32 v230, v73, v230
	v_exp_f32_e32 v76, v76
	v_add_f32_e32 v230, v74, v230
	v_exp_f32_e32 v77, v77
	v_cvt_pk_fp8_f32 v122, v72, v73
	v_add_f32_e32 v230, v75, v230
	v_exp_f32_e32 v78, v78
	v_add_f32_e32 v230, v76, v230
	v_exp_f32_e32 v79, v79
	v_cvt_pk_fp8_f32 v122, v74, v75 op_sel:[0,0,1]
	v_add_f32_e32 v230, v77, v230
	v_exp_f32_e32 v80, v80
	v_add_f32_e32 v230, v78, v230
	v_exp_f32_e32 v81, v81
	v_cvt_pk_fp8_f32 v123, v76, v77
	v_add_f32_e32 v230, v79, v230
	v_exp_f32_e32 v82, v82
	v_add_f32_e32 v230, v80, v230
	v_exp_f32_e32 v83, v83
	v_cvt_pk_fp8_f32 v123, v78, v79 op_sel:[0,0,1]
	v_add_f32_e32 v230, v81, v230
	v_exp_f32_e32 v84, v84
	v_add_f32_e32 v230, v82, v230
	v_exp_f32_e32 v85, v85
	v_cvt_pk_fp8_f32 v124, v80, v81
	v_add_f32_e32 v230, v83, v230
	v_exp_f32_e32 v86, v86
	v_add_f32_e32 v230, v84, v230
	v_exp_f32_e32 v87, v87
	v_cvt_pk_fp8_f32 v124, v82, v83 op_sel:[0,0,1]
	v_add_f32_e32 v230, v85, v230
	v_exp_f32_e32 v88, v88
	v_add_f32_e32 v230, v86, v230
	v_exp_f32_e32 v89, v89
	v_cvt_pk_fp8_f32 v125, v84, v85
	v_add_f32_e32 v230, v87, v230
	v_exp_f32_e32 v90, v90
	v_add_f32_e32 v230, v88, v230
	v_exp_f32_e32 v91, v91
	v_cvt_pk_fp8_f32 v125, v86, v87 op_sel:[0,0,1]
	v_add_f32_e32 v230, v89, v230
	v_exp_f32_e32 v92, v92
	v_add_f32_e32 v230, v90, v230
	v_exp_f32_e32 v93, v93
	v_cvt_pk_fp8_f32 v126, v88, v89
	v_add_f32_e32 v230, v91, v230
	v_exp_f32_e32 v94, v94
	v_add_f32_e32 v230, v92, v230
	v_exp_f32_e32 v95, v95
	v_cvt_pk_fp8_f32 v126, v90, v91 op_sel:[0,0,1]
	v_add_f32_e32 v230, v93, v230
	v_add_f32_e32 v230, v94, v230
	v_cvt_pk_fp8_f32 v127, v92, v93
	v_add_f32_e32 v230, v95, v230
	v_cvt_pk_fp8_f32 v127, v94, v95 op_sel:[0,0,1]
	v_fma_f32 v194, v194, v226, v230
	s_waitcnt lgkmcnt(0)
	s_barrier
	s_add_u32 s6, s6, 1
	s_add_u32 s4, s6, 2
	ds_read_b128 v[176:179], v221 offset:20480
	ds_read_b128 v[180:183], v221 offset:20496
	ds_read_b128 v[184:187], v221 offset:23040
	ds_read_b128 v[188:191], v221 offset:23056
	s_waitcnt lgkmcnt(4)
	v_mfma_scale_f32_32x32x64_f8f6f4 v[64:79], v[128:135], v[96:103], v[160:175], v235, v201 op_sel_hi:[0,0,0]
	ds_read_b128 v[128:131], v220 offset:40064
	ds_read_b128 v[132:135], v220 offset:40080
	v_mfma_scale_f32_32x32x64_f8f6f4 v[80:95], v[136:143], v[96:103], v[160:175], v235, v201 op_sel_hi:[0,0,0]
	ds_read_b128 v[136:139], v220 offset:46720
	ds_read_b128 v[140:143], v220 offset:46736
	s_cmp_lt_u32 s4, 128
	s_cbranch_scc0 .Latt_ms3_r0_nowr
	s_waitcnt vmcnt(0)
	ds_write2_b32 v224, v202, v204 offset1:1
	ds_write2_b32 v224, v203, v205 offset0:8 offset1:9
	ds_write_b128 v218, v[206:209] offset:13312
	ds_write_b128 v219, v[210:213] offset:13312
.Latt_ms3_r0_nowr:
	v_mfma_scale_f32_32x32x64_f8f6f4 v[64:79], v[144:151], v[104:111], v[64:79], v235, v201 op_sel_hi:[0,0,0]
	ds_read_b128 v[144:147], v220 offset:64
	ds_read_b128 v[148:151], v220 offset:80
	v_mfma_scale_f32_32x32x64_f8f6f4 v[80:95], v[152:159], v[104:111], v[80:95], v235, v201 op_sel_hi:[0,0,0]
	ds_read_b128 v[152:155], v220 offset:6720
	ds_read_b128 v[156:159], v220 offset:6736
	s_cmp_lt_u32 s4, 127
	s_cbranch_scc0 .Latt_ms3_r0_nold
	global_load_dwordx4 v[202:205], v216, s[10:11]
	global_load_dwordx4 v[206:209], v214, s[8:9]
	global_load_dwordx4 v[210:213], v215, s[8:9]
	s_add_u32 s8, s8, 0x3000
	s_addc_u32 s9, s9, 0
	s_add_u32 s10, s10, 64
	s_addc_u32 s11, s11, 0

; #define SLOAD(i, k0) do { sr_[i].vs = *(const u32x4*)(vsrc + (k0)); \
;     { const unsigned char* kt_ = Kh + (size_t)(k0) * 192; sr_[i].ks0 = *(const u32x4*)(kt_ + tid * 16); if (k2) sr_[i].ks1 = *(const u32x4*)(kt_ + 8192 + tid * 16); } } while (0)
; __device__ __forceinline__ void attn_body(const unsigned char* __restrict__ Qb, const unsigned char* __restrict__ Kh, const unsigned char* __restrict__ Vt,
;                                           bf16_t* __restrict__ Ob, int seq, char* lds) {
;     ...
;   int sP = 0, sC = 1, sN = 2;
;   SLOAD(0, 0); asm volatile("s_waitcnt vmcnt(0)" ::: "memory"); SWRITE(0, 0); SLOAD(0, KVBLK); __syncthreads();
;   asm volatile("s_waitcnt vmcnt(0)" ::: "memory"); SWRITE(1, 0); if (2 < NT) SLOAD(0, 2 * KVBLK);
;   qkt(pA0, pA1, K_lds, qr, r32, hi); partialSM(pA0, pA1, m_reg, mnA, alA);
;   for (int j = 1; j + 1 < NT; j += 2) {
;     STEP(j, pB0, pB1, mnB, alB, pA0, pA1, alA);
;     STEP(j + 1, pA0, pA1, mnA, alA, pB0, pB1, alB);
;   }
.Latt_m_done_3_r0:
	s_nop 3
	v_max3_f32 v228, v64, v65, v66
	v_max3_f32 v229, v80, v81, v82
	v_max3_f32 v228, v228, v67, v68
	v_max3_f32 v229, v229, v83, v84
	v_max3_f32 v228, v228, v69, v70
	v_max3_f32 v229, v229, v85, v86
	v_max3_f32 v228, v228, v71, v72
	v_max3_f32 v229, v229, v87, v88
	v_max3_f32 v228, v228, v73, v74
	v_max3_f32 v229, v229, v89, v90
	v_max3_f32 v228, v228, v75, v76
	v_max3_f32 v229, v229, v91, v92
	v_max3_f32 v228, v228, v77, v78
	v_max3_f32 v229, v229, v93, v94
	v_max3_f32 v228, v228, v79, v95
	v_max_f32_e32 v228, v228, v229
	s_mov_b32 s5, 3
	v_cmp_ge_f32_e32 vcc, s13, v228
	v_mov_b32_e32 v226, 1.0
	s_cmp_eq_u64 vcc, exec
	s_cbranch_scc0 .Latt_rare
.Latt_rare_back_3:
	v_exp_f32_e32 v64, v64
	v_exp_f32_e32 v65, v65
	v_exp_f32_e32 v66, v66
	v_exp_f32_e32 v67, v67
	v_add_f32_e32 v230, v64, v65
	v_exp_f32_e32 v68, v68
	v_add_f32_e32 v230, v66, v230
	v_exp_f32_e32 v69, v69
	v_cvt_pk_fp8_f32 v120, v64, v65
	v_add_f32_e32 v230, v67, v230
	v_exp_f32_e32 v70, v70
	v_add_f32_e32 v230, v68, v230
	v_exp_f32_e32 v71, v71
	v_cvt_pk_fp8_f32 v120, v66, v67 op_sel:[0,0,1]
	v_add_f32_e32 v230, v69, v230
	v_exp_f32_e32 v72, v72
	v_add_f32_e32 v230, v70, v230
	v_exp_f32_e32 v73, v73
	v_cvt_pk_fp8_f32 v121, v68, v69
	v_add_f32_e32 v230, v71, v230
	v_exp_f32_e32 v74, v74
	v_add_f32_e32 v230, v72, v230
	v_exp_f32_e32 v75, v75
	v_cvt_pk_fp8_f32 v121, v70, v71 op_sel:[0,0,1]
	v_add_f32_e32 v230, v73, v230
	v_exp_f32_e32 v76, v76
	v_add_f32_e32 v230, v74, v230
	v_exp_f32_e32 v77, v77
	v_cvt_pk_fp8_f32 v122, v72, v73
	v_add_f32_e32 v230, v75, v230
	v_exp_f32_e32 v78, v78
	v_add_f32_e32 v230, v76, v230
	v_exp_f32_e32 v79, v79
	v_cvt_pk_fp8_f32 v122, v74, v75 op_sel:[0,0,1]
	v_add_f32_e32 v230, v77, v230
	v_exp_f32_e32 v80, v80
	v_add_f32_e32 v230, v78, v230
	v_exp_f32_e32 v81, v81
	v_cvt_pk_fp8_f32 v123, v76, v77
	v_add_f32_e32 v230, v79, v230
	v_exp_f32_e32 v82, v82
	v_add_f32_e32 v230, v80, v230
	v_exp_f32_e32 v83, v83
	v_cvt_pk_fp8_f32 v123, v78, v79 op_sel:[0,0,1]
	v_add_f32_e32 v230, v81, v230
	v_exp_f32_e32 v84, v84
	v_add_f32_e32 v230, v82, v230
	v_exp_f32_e32 v85, v85
	v_cvt_pk_fp8_f32 v124, v80, v81
	v_add_f32_e32 v230, v83, v230
	v_exp_f32_e32 v86, v86
	v_add_f32_e32 v230, v84, v230
	v_exp_f32_e32 v87, v87
	v_cvt_pk_fp8_f32 v124, v82, v83 op_sel:[0,0,1]
	v_add_f32_e32 v230, v85, v230
	v_exp_f32_e32 v88, v88
	v_add_f32_e32 v230, v86, v230
	v_exp_f32_e32 v89, v89
	v_cvt_pk_fp8_f32 v125, v84, v85
	v_add_f32_e32 v230, v87, v230
	v_exp_f32_e32 v90, v90
	v_add_f32_e32 v230, v88, v230
	v_exp_f32_e32 v91, v91
	v_cvt_pk_fp8_f32 v125, v86, v87 op_sel:[0,0,1]
	v_add_f32_e32 v230, v89, v230
	v_exp_f32_e32 v92, v92
	v_add_f32_e32 v230, v90, v230
	v_exp_f32_e32 v93, v93
	v_cvt_pk_fp8_f32 v126, v88, v89
	v_add_f32_e32 v230, v91, v230
	v_exp_f32_e32 v94, v94
	v_add_f32_e32 v230, v92, v230
	v_exp_f32_e32 v95, v95
	v_cvt_pk_fp8_f32 v126, v90, v91 op_sel:[0,0,1]
	v_add_f32_e32 v230, v93, v230
	v_add_f32_e32 v230, v94, v230
	v_cvt_pk_fp8_f32 v127, v92, v93
	v_add_f32_e32 v230, v95, v230
	v_cvt_pk_fp8_f32 v127, v94, v95 op_sel:[0,0,1]
	v_fma_f32 v194, v194, v226, v230
	s_waitcnt lgkmcnt(0)
	s_barrier
	s_add_u32 s6, s6, 1
	s_cmp_lt_u32 s6, 128
	s_cbranch_scc1 .Latt_loop_r0
	s_branch .Latt_tail
.Latt_tramp12:
	s_branch .LBB0_12
.Latt_loop_r1:
	s_cmp_eq_u32 s6, 0
	s_cbranch_scc1 .Latt_m_first_r1
	s_add_u32 s4, s6, 2
	ds_read_b128 v[176:179], v221 offset:30720
	ds_read_b128 v[180:183], v221 offset:30736
	ds_read_b128 v[184:187], v221 offset:33280
	ds_read_b128 v[188:191], v221 offset:33296
	s_waitcnt lgkmcnt(4)
	v_mfma_scale_f32_32x32x64_f8f6f4 v[64:79], v[128:135], v[96:103], v[160:175], v235, v201 op_sel_hi:[0,0,0]
	ds_read_b128 v[128:131], v220 offset:128
	ds_read_b128 v[132:135], v220 offset:144
	v_mfma_scale_f32_32x32x64_f8f6f4 v[80:95], v[136:143], v[96:103], v[160:175], v235, v201 op_sel_hi:[0,0,0]
	ds_read_b128 v[136:139], v220 offset:6784
	ds_read_b128 v[140:143], v220 offset:6800
	s_cmp_lt_u32 s4, 128
	s_cbranch_scc0 .Latt_ms0_r1_nowr
	s_waitcnt vmcnt(0)
	ds_write2_b32 v225, v202, v204 offset1:1
	ds_write2_b32 v225, v203, v205 offset0:8 offset1:9
	ds_write_b128 v218, v[206:209] offset:26624
.Latt_ms0_r1_nowr:
	v_mfma_scale_f32_32x32x64_f8f6f4 v[64:79], v[144:151], v[104:111], v[64:79], v235, v201 op_sel_hi:[0,0,0]
	ds_read_b128 v[144:147], v220 offset:13376
	ds_read_b128 v[148:151], v220 offset:13392
	v_mfma_scale_f32_32x32x64_f8f6f4 v[80:95], v[152:159], v[104:111], v[80:95], v235, v201 op_sel_hi:[0,0,0]
	ds_read_b128 v[152:155], v220 offset:20032
	ds_read_b128 v[156:159], v220 offset:20048
	s_cmp_lt_u32 s4, 127
	s_cbranch_scc0 .Latt_ms0_r1_nold
	global_load_dwordx4 v[202:205], v216, s[10:11]
	global_load_dwordx4 v[206:209], v214, s[8:9]
	s_add_u32 s8, s8, 0x3000
	s_addc_u32 s9, s9, 0
	s_add_u32 s10, s10, 64
	s_addc_u32 s11, s11, 0

; __device__ __forceinline__ void partialSM(f32x16& p0, f32x16& p1, float& m_reg, float& mn, float& alpha) {
;   constexpr float C = SCALE * 1.4426950408889634f;
;   float pmax = p0[0]; for (int r = 1; r < 16; ++r) pmax = fmaxf(pmax, p0[r]); for (int r = 0; r < 16; ++r) pmax = fmaxf(pmax, p1[r]);
;   { auto rr = __builtin_amdgcn_permlane32_swap(__float_as_uint(pmax), __float_as_uint(pmax), false, false);
;     pmax = fmaxf(__uint_as_float(rr[0]), __uint_as_float(rr[1])); }
;   if (__builtin_expect(__all(pmax - m_reg <= THR / SCALE), 1)) { mn = m_reg; alpha = 1.f; }
;   else { mn = fmaxf(m_reg, pmax); alpha = __builtin_amdgcn_exp2f((m_reg - mn) * C); m_reg = mn; }
;   float mnC = -mn * C + 5.f;
;   for (int r = 0; r < 16; ++r) p0[r] = fmaf(p0[r], C, mnC); for (int r = 0; r < 16; ++r) p1[r] = fmaf(p1[r], C, mnC);
;   for (int r = 0; r < 16; ++r) p0[r] = __builtin_amdgcn_exp2f(p0[r]);
; }
; __device__ __forceinline__ void finishSM(f32x16& p0, f32x16& p1, float alpha, float& l_reg, i32x8& pa) {
;   for (int r = 0; r < 16; ++r) p1[r] = __builtin_amdgcn_exp2f(p1[r]);
;   float ps = 0; for (int r = 0; r < 16; ++r) ps += p0[r]; for (int r = 0; r < 16; ++r) ps += p1[r];
;   { auto rr = __builtin_amdgcn_permlane32_swap(__float_as_uint(ps), __float_as_uint(ps), false, false);
;     ps = __uint_as_float(rr[0]) + __uint_as_float(rr[1]); }
;   l_reg = l_reg * alpha + ps;
; #pragma unroll
;   for (int i = 0; i < 4; ++i) { int w0 = 0, w1 = 0;
;     w0 = __builtin_amdgcn_cvt_pk_fp8_f32(p0[4 * i], p0[4 * i + 1], w0, false); w0 = __builtin_amdgcn_cvt_pk_fp8_f32(p0[4 * i + 2], p0[4 * i + 3], w0, true);
;     w1 = __builtin_amdgcn_cvt_pk_fp8_f32(p1[4 * i], p1[4 * i + 1], w1, false); w1 = __builtin_amdgcn_cvt_pk_fp8_f32(p1[4 * i + 2], p1[4 * i + 3], w1, true);
;     pa[i] = w0; pa[4 + i] = w1; }
; }
.Latt_m_done_0_r1:
	s_nop 3
	s_waitcnt lgkmcnt(0)
	s_barrier
	v_max3_f32 v228, v64, v65, v66
	v_max3_f32 v229, v80, v81, v82
	v_max3_f32 v228, v228, v67, v68
	v_max3_f32 v229, v229, v83, v84
	v_max3_f32 v228, v228, v69, v70
	v_max3_f32 v229, v229, v85, v86
	v_max3_f32 v228, v228, v71, v72
	v_max3_f32 v229, v229, v87, v88
	v_max3_f32 v228, v228, v73, v74
	v_max3_f32 v229, v229, v89, v90
	v_max3_f32 v228, v228, v75, v76
	v_max3_f32 v229, v229, v91, v92
	v_max3_f32 v228, v228, v77, v78
	v_max3_f32 v229, v229, v93, v94
	v_max3_f32 v228, v228, v79, v95
	v_max_f32_e32 v228, v228, v229
	s_mov_b32 s5, 4
	v_cmp_ge_f32_e32 vcc, s13, v228
	v_mov_b32_e32 v226, 1.0
	s_cmp_eq_u32 s6, 0
	s_cbranch_scc1 .Latt_rare
	s_cmp_eq_u64 vcc, exec
	s_cbranch_scc0 .Latt_rare
.Latt_rare_back_4:
	v_exp_f32_e32 v64, v64
	v_exp_f32_e32 v65, v65
	v_exp_f32_e32 v66, v66
	v_exp_f32_e32 v67, v67
	v_add_f32_e32 v230, v64, v65
	v_exp_f32_e32 v68, v68
	v_add_f32_e32 v230, v66, v230
	v_exp_f32_e32 v69, v69
	v_cvt_pk_fp8_f32 v120, v64, v65
	v_add_f32_e32 v230, v67, v230
	v_exp_f32_e32 v70, v70
	v_add_f32_e32 v230, v68, v230
	v_exp_f32_e32 v71, v71
	v_cvt_pk_fp8_f32 v120, v66, v67 op_sel:[0,0,1]
	v_add_f32_e32 v230, v69, v230
	v_exp_f32_e32 v72, v72
	v_add_f32_e32 v230, v70, v230
	v_exp_f32_e32 v73, v73
	v_cvt_pk_fp8_f32 v121, v68, v69
	v_add_f32_e32 v230, v71, v230
	v_exp_f32_e32 v74, v74
	v_add_f32_e32 v230, v72, v230
	v_exp_f32_e32 v75, v75
	v_cvt_pk_fp8_f32 v121, v70, v71 op_sel:[0,0,1]
	v_add_f32_e32 v230, v73, v230
	v_exp_f32_e32 v76, v76
	v_add_f32_e32 v230, v74, v230
	v_exp_f32_e32 v77, v77
	v_cvt_pk_fp8_f32 v122, v72, v73
	v_add_f32_e32 v230, v75, v230
	v_exp_f32_e32 v78, v78
	v_add_f32_e32 v230, v76, v230
	v_exp_f32_e32 v79, v79
	v_cvt_pk_fp8_f32 v122, v74, v75 op_sel:[0,0,1]
	v_add_f32_e32 v230, v77, v230
	v_exp_f32_e32 v80, v80
	v_add_f32_e32 v230, v78, v230
	v_exp_f32_e32 v81, v81
	v_cvt_pk_fp8_f32 v123, v76, v77
	v_add_f32_e32 v230, v79, v230
	v_exp_f32_e32 v82, v82
	v_add_f32_e32 v230, v80, v230
	v_exp_f32_e32 v83, v83
	v_cvt_pk_fp8_f32 v123, v78, v79 op_sel:[0,0,1]
	v_add_f32_e32 v230, v81, v230
	v_exp_f32_e32 v84, v84
	v_add_f32_e32 v230, v82, v230
	v_exp_f32_e32 v85, v85
	v_cvt_pk_fp8_f32 v124, v80, v81
	v_add_f32_e32 v230, v83, v230
	v_exp_f32_e32 v86, v86
	v_add_f32_e32 v230, v84, v230
	v_exp_f32_e32 v87, v87
	v_cvt_pk_fp8_f32 v124, v82, v83 op_sel:[0,0,1]
	v_add_f32_e32 v230, v85, v230
	v_exp_f32_e32 v88, v88
	v_add_f32_e32 v230, v86, v230
	v_exp_f32_e32 v89, v89
	v_cvt_pk_fp8_f32 v125, v84, v85
	v_add_f32_e32 v230, v87, v230
	v_exp_f32_e32 v90, v90
	v_add_f32_e32 v230, v88, v230
	v_exp_f32_e32 v91, v91
	v_cvt_pk_fp8_f32 v125, v86, v87 op_sel:[0,0,1]
	v_add_f32_e32 v230, v89, v230
	v_exp_f32_e32 v92, v92
	v_add_f32_e32 v230, v90, v230
	v_exp_f32_e32 v93, v93
	v_cvt_pk_fp8_f32 v126, v88, v89
	v_add_f32_e32 v230, v91, v230
	v_exp_f32_e32 v94, v94
	v_add_f32_e32 v230, v92, v230
	v_exp_f32_e32 v95, v95
	v_cvt_pk_fp8_f32 v126, v90, v91 op_sel:[0,0,1]
	v_add_f32_e32 v230, v93, v230
	v_add_f32_e32 v230, v94, v230
	v_cvt_pk_fp8_f32 v127, v92, v93
	v_add_f32_e32 v230, v95, v230
	v_cvt_pk_fp8_f32 v127, v94, v95 op_sel:[0,0,1]
	v_fma_f32 v194, v194, v226, v230
	s_waitcnt lgkmcnt(0)
	s_add_u32 s6, s6, 1
	s_add_u32 s4, s6, 2
	ds_read_b128 v[176:179], v221 offset:0
	ds_read_b128 v[180:183], v221 offset:16
	ds_read_b128 v[184:187], v221 offset:2560
	ds_read_b128 v[188:191], v221 offset:2576
	s_waitcnt lgkmcnt(4)
	v_mfma_scale_f32_32x32x64_f8f6f4 v[64:79], v[128:135], v[96:103], v[160:175], v235, v201 op_sel_hi:[0,0,0]
	ds_read_b128 v[128:131], v220 offset:13440
	ds_read_b128 v[132:135], v220 offset:13456
	v_mfma_scale_f32_32x32x64_f8f6f4 v[80:95], v[136:143], v[96:103], v[160:175], v235, v201 op_sel_hi:[0,0,0]
	ds_read_b128 v[136:139], v220 offset:20096
	ds_read_b128 v[140:143], v220 offset:20112
	s_cmp_lt_u32 s4, 128
	s_cbranch_scc0 .Latt_ms1_r1_nowr
	v_add_u32_e32 v228, 30720, v217
	s_waitcnt vmcnt(0)
	ds_write2_b32 v228, v202, v204 offset1:1
	ds_write2_b32 v228, v203, v205 offset0:8 offset1:9
	ds_write_b128 v218, v[206:209] offset:39936
.Latt_ms1_r1_nowr:
	v_mfma_scale_f32_32x32x64_f8f6f4 v[64:79], v[144:151], v[104:111], v[64:79], v235, v201 op_sel_hi:[0,0,0]
	ds_read_b128 v[144:147], v220 offset:26688
	ds_read_b128 v[148:151], v220 offset:26704
	v_mfma_scale_f32_32x32x64_f8f6f4 v[80:95], v[152:159], v[104:111], v[80:95], v235, v201 op_sel_hi:[0,0,0]
	ds_read_b128 v[152:155], v220 offset:33344
	ds_read_b128 v[156:159], v220 offset:33360
	s_cmp_lt_u32 s4, 127
	s_cbranch_scc0 .Latt_ms1_r1_nold
	global_load_dwordx4 v[202:205], v216, s[10:11]
	global_load_dwordx4 v[206:209], v214, s[8:9]
	s_add_u32 s8, s8, 0x3000
	s_addc_u32 s9, s9, 0
	s_add_u32 s10, s10, 64
	s_addc_u32 s11, s11, 0

; __device__ __forceinline__ void partialSM(f32x16& p0, f32x16& p1, float& m_reg, float& mn, float& alpha) {
;   constexpr float C = SCALE * 1.4426950408889634f;
;   float pmax = p0[0]; for (int r = 1; r < 16; ++r) pmax = fmaxf(pmax, p0[r]); for (int r = 0; r < 16; ++r) pmax = fmaxf(pmax, p1[r]);
;   { auto rr = __builtin_amdgcn_permlane32_swap(__float_as_uint(pmax), __float_as_uint(pmax), false, false);
;     pmax = fmaxf(__uint_as_float(rr[0]), __uint_as_float(rr[1])); }
;   if (__builtin_expect(__all(pmax - m_reg <= THR / SCALE), 1)) { mn = m_reg; alpha = 1.f; }
;   else { mn = fmaxf(m_reg, pmax); alpha = __builtin_amdgcn_exp2f((m_reg - mn) * C); m_reg = mn; }
;   float mnC = -mn * C + 5.f;
;   for (int r = 0; r < 16; ++r) p0[r] = fmaf(p0[r], C, mnC); for (int r = 0; r < 16; ++r) p1[r] = fmaf(p1[r], C, mnC);
;   for (int r = 0; r < 16; ++r) p0[r] = __builtin_amdgcn_exp2f(p0[r]);
; }
; __device__ __forceinline__ void finishSM(f32x16& p0, f32x16& p1, float alpha, float& l_reg, i32x8& pa) {
;   for (int r = 0; r < 16; ++r) p1[r] = __builtin_amdgcn_exp2f(p1[r]);
;   float ps = 0; for (int r = 0; r < 16; ++r) ps += p0[r]; for (int r = 0; r < 16; ++r) ps += p1[r];
;   { auto rr = __builtin_amdgcn_permlane32_swap(__float_as_uint(ps), __float_as_uint(ps), false, false);
;     ps = __uint_as_float(rr[0]) + __uint_as_float(rr[1]); }
;   l_reg = l_reg * alpha + ps;
; #pragma unroll
;   for (int i = 0; i < 4; ++i) { int w0 = 0, w1 = 0;
;     w0 = __builtin_amdgcn_cvt_pk_fp8_f32(p0[4 * i], p0[4 * i + 1], w0, false); w0 = __builtin_amdgcn_cvt_pk_fp8_f32(p0[4 * i + 2], p0[4 * i + 3], w0, true);
;     w1 = __builtin_amdgcn_cvt_pk_fp8_f32(p1[4 * i], p1[4 * i + 1], w1, false); w1 = __builtin_amdgcn_cvt_pk_fp8_f32(p1[4 * i + 2], p1[4 * i + 3], w1, true);
;     pa[i] = w0; pa[4 + i] = w1; }
; }
.Latt_m_done_1_r1:
	s_nop 3
	s_waitcnt lgkmcnt(0)
	s_barrier
	v_max3_f32 v228, v64, v65, v66
	v_max3_f32 v229, v80, v81, v82
	v_max3_f32 v228, v228, v67, v68
	v_max3_f32 v229, v229, v83, v84
	v_max3_f32 v228, v228, v69, v70
	v_max3_f32 v229, v229, v85, v86
	v_max3_f32 v228, v228, v71, v72
	v_max3_f32 v229, v229, v87, v88
	v_max3_f32 v228, v228, v73, v74
	v_max3_f32 v229, v229, v89, v90
	v_max3_f32 v228, v228, v75, v76
	v_max3_f32 v229, v229, v91, v92
	v_max3_f32 v228, v228, v77, v78
	v_max3_f32 v229, v229, v93, v94
	v_max3_f32 v228, v228, v79, v95
	v_max_f32_e32 v228, v228, v229
	s_mov_b32 s5, 5
	v_cmp_ge_f32_e32 vcc, s13, v228
	v_mov_b32_e32 v226, 1.0
	s_cmp_eq_u64 vcc, exec
	s_cbranch_scc0 .Latt_rare
.Latt_rare_back_5:
	v_exp_f32_e32 v64, v64
	v_exp_f32_e32 v65, v65
	v_exp_f32_e32 v66, v66
	v_exp_f32_e32 v67, v67
	v_add_f32_e32 v230, v64, v65
	v_exp_f32_e32 v68, v68
	v_add_f32_e32 v230, v66, v230
	v_exp_f32_e32 v69, v69
	v_cvt_pk_fp8_f32 v120, v64, v65
	v_add_f32_e32 v230, v67, v230
	v_exp_f32_e32 v70, v70
	v_add_f32_e32 v230, v68, v230
	v_exp_f32_e32 v71, v71
	v_cvt_pk_fp8_f32 v120, v66, v67 op_sel:[0,0,1]
	v_add_f32_e32 v230, v69, v230
	v_exp_f32_e32 v72, v72
	v_add_f32_e32 v230, v70, v230
	v_exp_f32_e32 v73, v73
	v_cvt_pk_fp8_f32 v121, v68, v69
	v_add_f32_e32 v230, v71, v230
	v_exp_f32_e32 v74, v74
	v_add_f32_e32 v230, v72, v230
	v_exp_f32_e32 v75, v75
	v_cvt_pk_fp8_f32 v121, v70, v71 op_sel:[0,0,1]
	v_add_f32_e32 v230, v73, v230
	v_exp_f32_e32 v76, v76
	v_add_f32_e32 v230, v74, v230
	v_exp_f32_e32 v77, v77
	v_cvt_pk_fp8_f32 v122, v72, v73
	v_add_f32_e32 v230, v75, v230
	v_exp_f32_e32 v78, v78
	v_add_f32_e32 v230, v76, v230
	v_exp_f32_e32 v79, v79
	v_cvt_pk_fp8_f32 v122, v74, v75 op_sel:[0,0,1]
	v_add_f32_e32 v230, v77, v230
	v_exp_f32_e32 v80, v80
	v_add_f32_e32 v230, v78, v230
	v_exp_f32_e32 v81, v81
	v_cvt_pk_fp8_f32 v123, v76, v77
	v_add_f32_e32 v230, v79, v230
	v_exp_f32_e32 v82, v82
	v_add_f32_e32 v230, v80, v230
	v_exp_f32_e32 v83, v83
	v_cvt_pk_fp8_f32 v123, v78, v79 op_sel:[0,0,1]
	v_add_f32_e32 v230, v81, v230
	v_exp_f32_e32 v84, v84
	v_add_f32_e32 v230, v82, v230
	v_exp_f32_e32 v85, v85
	v_cvt_pk_fp8_f32 v124, v80, v81
	v_add_f32_e32 v230, v83, v230
	v_exp_f32_e32 v86, v86
	v_add_f32_e32 v230, v84, v230
	v_exp_f32_e32 v87, v87
	v_cvt_pk_fp8_f32 v124, v82, v83 op_sel:[0,0,1]
	v_add_f32_e32 v230, v85, v230
	v_exp_f32_e32 v88, v88
	v_add_f32_e32 v230, v86, v230
	v_exp_f32_e32 v89, v89
	v_cvt_pk_fp8_f32 v125, v84, v85
	v_add_f32_e32 v230, v87, v230
	v_exp_f32_e32 v90, v90
	v_add_f32_e32 v230, v88, v230
	v_exp_f32_e32 v91, v91
	v_cvt_pk_fp8_f32 v125, v86, v87 op_sel:[0,0,1]
	v_add_f32_e32 v230, v89, v230
	v_exp_f32_e32 v92, v92
	v_add_f32_e32 v230, v90, v230
	v_exp_f32_e32 v93, v93
	v_cvt_pk_fp8_f32 v126, v88, v89
	v_add_f32_e32 v230, v91, v230
	v_exp_f32_e32 v94, v94
	v_add_f32_e32 v230, v92, v230
	v_exp_f32_e32 v95, v95
	v_cvt_pk_fp8_f32 v126, v90, v91 op_sel:[0,0,1]
	v_add_f32_e32 v230, v93, v230
	v_add_f32_e32 v230, v94, v230
	v_cvt_pk_fp8_f32 v127, v92, v93
	v_add_f32_e32 v230, v95, v230
	v_cvt_pk_fp8_f32 v127, v94, v95 op_sel:[0,0,1]
	v_fma_f32 v194, v194, v226, v230
	s_waitcnt lgkmcnt(0)
	s_add_u32 s6, s6, 1
	s_add_u32 s4, s6, 2
	ds_read_b128 v[176:179], v221 offset:10240
	ds_read_b128 v[180:183], v221 offset:10256
	ds_read_b128 v[184:187], v221 offset:12800
	ds_read_b128 v[188:191], v221 offset:12816
	s_waitcnt lgkmcnt(4)
	v_mfma_scale_f32_32x32x64_f8f6f4 v[64:79], v[128:135], v[96:103], v[160:175], v235, v201 op_sel_hi:[0,0,0]
	ds_read_b128 v[128:131], v220 offset:26752
	ds_read_b128 v[132:135], v220 offset:26768
	v_mfma_scale_f32_32x32x64_f8f6f4 v[80:95], v[136:143], v[96:103], v[160:175], v235, v201 op_sel_hi:[0,0,0]
	ds_read_b128 v[136:139], v220 offset:33408
	ds_read_b128 v[140:143], v220 offset:33424
	s_cmp_lt_u32 s4, 128
	s_cbranch_scc0 .Latt_ms2_r1_nowr
	s_waitcnt vmcnt(0)
	ds_write2_b32 v217, v202, v204 offset1:1
	ds_write2_b32 v217, v203, v205 offset0:8 offset1:9
	ds_write_b128 v218, v[206:209] offset:0
.Latt_ms2_r1_nowr:
	v_mfma_scale_f32_32x32x64_f8f6f4 v[64:79], v[144:151], v[104:111], v[64:79], v235, v201 op_sel_hi:[0,0,0]
	ds_read_b128 v[144:147], v220 offset:40000
	ds_read_b128 v[148:151], v220 offset:40016
	v_mfma_scale_f32_32x32x64_f8f6f4 v[80:95], v[152:159], v[104:111], v[80:95], v235, v201 op_sel_hi:[0,0,0]
	ds_read_b128 v[152:155], v220 offset:46656
	ds_read_b128 v[156:159], v220 offset:46672
	s_cmp_lt_u32 s4, 127
	s_cbranch_scc0 .Latt_ms2_r1_nold
	global_load_dwordx4 v[202:205], v216, s[10:11]
	global_load_dwordx4 v[206:209], v214, s[8:9]
	s_add_u32 s8, s8, 0x3000
	s_addc_u32 s9, s9, 0
	s_add_u32 s10, s10, 64
	s_addc_u32 s11, s11, 0

; __device__ __forceinline__ void partialSM(f32x16& p0, f32x16& p1, float& m_reg, float& mn, float& alpha) {
;   constexpr float C = SCALE * 1.4426950408889634f;
;   float pmax = p0[0]; for (int r = 1; r < 16; ++r) pmax = fmaxf(pmax, p0[r]); for (int r = 0; r < 16; ++r) pmax = fmaxf(pmax, p1[r]);
;   { auto rr = __builtin_amdgcn_permlane32_swap(__float_as_uint(pmax), __float_as_uint(pmax), false, false);
;     pmax = fmaxf(__uint_as_float(rr[0]), __uint_as_float(rr[1])); }
;   if (__builtin_expect(__all(pmax - m_reg <= THR / SCALE), 1)) { mn = m_reg; alpha = 1.f; }
;   else { mn = fmaxf(m_reg, pmax); alpha = __builtin_amdgcn_exp2f((m_reg - mn) * C); m_reg = mn; }
;   float mnC = -mn * C + 5.f;
;   for (int r = 0; r < 16; ++r) p0[r] = fmaf(p0[r], C, mnC); for (int r = 0; r < 16; ++r) p1[r] = fmaf(p1[r], C, mnC);
;   for (int r = 0; r < 16; ++r) p0[r] = __builtin_amdgcn_exp2f(p0[r]);
; }
; __device__ __forceinline__ void finishSM(f32x16& p0, f32x16& p1, float alpha, float& l_reg, i32x8& pa) {
;   for (int r = 0; r < 16; ++r) p1[r] = __builtin_amdgcn_exp2f(p1[r]);
;   float ps = 0; for (int r = 0; r < 16; ++r) ps += p0[r]; for (int r = 0; r < 16; ++r) ps += p1[r];
;   { auto rr = __builtin_amdgcn_permlane32_swap(__float_as_uint(ps), __float_as_uint(ps), false, false);
;     ps = __uint_as_float(rr[0]) + __uint_as_float(rr[1]); }
;   l_reg = l_reg * alpha + ps;
; #pragma unroll
;   for (int i = 0; i < 4; ++i) { int w0 = 0, w1 = 0;
;     w0 = __builtin_amdgcn_cvt_pk_fp8_f32(p0[4 * i], p0[4 * i + 1], w0, false); w0 = __builtin_amdgcn_cvt_pk_fp8_f32(p0[4 * i + 2], p0[4 * i + 3], w0, true);
;     w1 = __builtin_amdgcn_cvt_pk_fp8_f32(p1[4 * i], p1[4 * i + 1], w1, false); w1 = __builtin_amdgcn_cvt_pk_fp8_f32(p1[4 * i + 2], p1[4 * i + 3], w1, true);
;     pa[i] = w0; pa[4 + i] = w1; }
; }
; __device__ __forceinline__ void qkt(f32x16& p0, f32x16& p1, const unsigned char* Ks, const i32x8* qr, int r32, int hi) {
;   p0 = f32x16{}; p1 = f32x16{};
; #pragma unroll
;   for (int m = 0; m < 3; ++m) { const int cb = m * 64 + hi * 32;
;     const u32x4 a0 = *reinterpret_cast<const u32x4*>(Ks + KSWZ(r32, cb)), a1 = *reinterpret_cast<const u32x4*>(Ks + KSWZ(r32, cb) + 16);
;     const u32x4 c0 = *reinterpret_cast<const u32x4*>(Ks + KSWZ(32 + r32, cb)), c1 = *reinterpret_cast<const u32x4*>(Ks + KSWZ(32 + r32, cb) + 16);
.Latt_m_done_2_r1:
	s_nop 3
	s_waitcnt lgkmcnt(0)
	s_barrier
	v_max3_f32 v228, v64, v65, v66
	v_max3_f32 v229, v80, v81, v82
	v_max3_f32 v228, v228, v67, v68
	v_max3_f32 v229, v229, v83, v84
	v_max3_f32 v228, v228, v69, v70
	v_max3_f32 v229, v229, v85, v86
	v_max3_f32 v228, v228, v71, v72
	v_max3_f32 v229, v229, v87, v88
	v_max3_f32 v228, v228, v73, v74
	v_max3_f32 v229, v229, v89, v90
	v_max3_f32 v228, v228, v75, v76
	v_max3_f32 v229, v229, v91, v92
	v_max3_f32 v228, v228, v77, v78
	v_max3_f32 v229, v229, v93, v94
	v_max3_f32 v228, v228, v79, v95
	v_max_f32_e32 v228, v228, v229
	s_mov_b32 s5, 6
	v_cmp_ge_f32_e32 vcc, s13, v228
	v_mov_b32_e32 v226, 1.0
	s_cmp_eq_u64 vcc, exec
	s_cbranch_scc0 .Latt_rare
.Latt_rare_back_6:
	v_exp_f32_e32 v64, v64
	v_exp_f32_e32 v65, v65
	v_exp_f32_e32 v66, v66
	v_exp_f32_e32 v67, v67
	v_add_f32_e32 v230, v64, v65
	v_exp_f32_e32 v68, v68
	v_add_f32_e32 v230, v66, v230
	v_exp_f32_e32 v69, v69
	v_cvt_pk_fp8_f32 v120, v64, v65
	v_add_f32_e32 v230, v67, v230
	v_exp_f32_e32 v70, v70
	v_add_f32_e32 v230, v68, v230
	v_exp_f32_e32 v71, v71
	v_cvt_pk_fp8_f32 v120, v66, v67 op_sel:[0,0,1]
	v_add_f32_e32 v230, v69, v230
	v_exp_f32_e32 v72, v72
	v_add_f32_e32 v230, v70, v230
	v_exp_f32_e32 v73, v73
	v_cvt_pk_fp8_f32 v121, v68, v69
	v_add_f32_e32 v230, v71, v230
	v_exp_f32_e32 v74, v74
	v_add_f32_e32 v230, v72, v230
	v_exp_f32_e32 v75, v75
	v_cvt_pk_fp8_f32 v121, v70, v71 op_sel:[0,0,1]
	v_add_f32_e32 v230, v73, v230
	v_exp_f32_e32 v76, v76
	v_add_f32_e32 v230, v74, v230
	v_exp_f32_e32 v77, v77
	v_cvt_pk_fp8_f32 v122, v72, v73
	v_add_f32_e32 v230, v75, v230
	v_exp_f32_e32 v78, v78
	v_add_f32_e32 v230, v76, v230
	v_exp_f32_e32 v79, v79
	v_cvt_pk_fp8_f32 v122, v74, v75 op_sel:[0,0,1]
	v_add_f32_e32 v230, v77, v230
	v_exp_f32_e32 v80, v80
	v_add_f32_e32 v230, v78, v230
	v_exp_f32_e32 v81, v81
	v_cvt_pk_fp8_f32 v123, v76, v77
	v_add_f32_e32 v230, v79, v230
	v_exp_f32_e32 v82, v82
	v_add_f32_e32 v230, v80, v230
	v_exp_f32_e32 v83, v83
	v_cvt_pk_fp8_f32 v123, v78, v79 op_sel:[0,0,1]
	v_add_f32_e32 v230, v81, v230
	v_exp_f32_e32 v84, v84
	v_add_f32_e32 v230, v82, v230
	v_exp_f32_e32 v85, v85
	v_cvt_pk_fp8_f32 v124, v80, v81
	v_add_f32_e32 v230, v83, v230
	v_exp_f32_e32 v86, v86
	v_add_f32_e32 v230, v84, v230
	v_exp_f32_e32 v87, v87
	v_cvt_pk_fp8_f32 v124, v82, v83 op_sel:[0,0,1]
	v_add_f32_e32 v230, v85, v230
	v_exp_f32_e32 v88, v88
	v_add_f32_e32 v230, v86, v230
	v_exp_f32_e32 v89, v89
	v_cvt_pk_fp8_f32 v125, v84, v85
	v_add_f32_e32 v230, v87, v230
	v_exp_f32_e32 v90, v90
	v_add_f32_e32 v230, v88, v230
	v_exp_f32_e32 v91, v91
	v_cvt_pk_fp8_f32 v125, v86, v87 op_sel:[0,0,1]
	v_add_f32_e32 v230, v89, v230
	v_exp_f32_e32 v92, v92
	v_add_f32_e32 v230, v90, v230
	v_exp_f32_e32 v93, v93
	v_cvt_pk_fp8_f32 v126, v88, v89
	v_add_f32_e32 v230, v91, v230
	v_exp_f32_e32 v94, v94
	v_add_f32_e32 v230, v92, v230
	v_exp_f32_e32 v95, v95
	v_cvt_pk_fp8_f32 v126, v90, v91 op_sel:[0,0,1]
	v_add_f32_e32 v230, v93, v230
	v_add_f32_e32 v230, v94, v230
	v_cvt_pk_fp8_f32 v127, v92, v93
	v_add_f32_e32 v230, v95, v230
	v_cvt_pk_fp8_f32 v127, v94, v95 op_sel:[0,0,1]
	v_fma_f32 v194, v194, v226, v230
	s_waitcnt lgkmcnt(0)
	s_add_u32 s6, s6, 1
	s_add_u32 s4, s6, 2
	ds_read_b128 v[176:179], v221 offset:20480
	ds_read_b128 v[180:183], v221 offset:20496
	ds_read_b128 v[184:187], v221 offset:23040
	ds_read_b128 v[188:191], v221 offset:23056
	s_waitcnt lgkmcnt(4)
	v_mfma_scale_f32_32x32x64_f8f6f4 v[64:79], v[128:135], v[96:103], v[160:175], v235, v201 op_sel_hi:[0,0,0]
	ds_read_b128 v[128:131], v220 offset:40064
	ds_read_b128 v[132:135], v220 offset:40080
	v_mfma_scale_f32_32x32x64_f8f6f4 v[80:95], v[136:143], v[96:103], v[160:175], v235, v201 op_sel_hi:[0,0,0]
	ds_read_b128 v[136:139], v220 offset:46720
	ds_read_b128 v[140:143], v220 offset:46736
	s_cmp_lt_u32 s4, 128
	s_cbranch_scc0 .Latt_ms3_r1_nowr
	s_waitcnt vmcnt(0)
	ds_write2_b32 v224, v202, v204 offset1:1
	ds_write2_b32 v224, v203, v205 offset0:8 offset1:9
	ds_write_b128 v218, v[206:209] offset:13312
.Latt_ms3_r1_nowr:
	v_mfma_scale_f32_32x32x64_f8f6f4 v[64:79], v[144:151], v[104:111], v[64:79], v235, v201 op_sel_hi:[0,0,0]
	ds_read_b128 v[144:147], v220 offset:64
	ds_read_b128 v[148:151], v220 offset:80
	v_mfma_scale_f32_32x32x64_f8f6f4 v[80:95], v[152:159], v[104:111], v[80:95], v235, v201 op_sel_hi:[0,0,0]
	ds_read_b128 v[152:155], v220 offset:6720
	ds_read_b128 v[156:159], v220 offset:6736
	s_cmp_lt_u32 s4, 127
	s_cbranch_scc0 .Latt_ms3_r1_nold
	global_load_dwordx4 v[202:205], v216, s[10:11]
	global_load_dwordx4 v[206:209], v214, s[8:9]
	s_add_u32 s8, s8, 0x3000
	s_addc_u32 s9, s9, 0
	s_add_u32 s10, s10, 64
	s_addc_u32 s11, s11, 0

; __device__ __forceinline__ void partialSM(f32x16& p0, f32x16& p1, float& m_reg, float& mn, float& alpha) {
;   constexpr float C = SCALE * 1.4426950408889634f;
;   float pmax = p0[0]; for (int r = 1; r < 16; ++r) pmax = fmaxf(pmax, p0[r]); for (int r = 0; r < 16; ++r) pmax = fmaxf(pmax, p1[r]);
;   { auto rr = __builtin_amdgcn_permlane32_swap(__float_as_uint(pmax), __float_as_uint(pmax), false, false);
;     pmax = fmaxf(__uint_as_float(rr[0]), __uint_as_float(rr[1])); }
;   if (__builtin_expect(__all(pmax - m_reg <= THR / SCALE), 1)) { mn = m_reg; alpha = 1.f; }
;   else { mn = fmaxf(m_reg, pmax); alpha = __builtin_amdgcn_exp2f((m_reg - mn) * C); m_reg = mn; }
;   float mnC = -mn * C + 5.f;
;   for (int r = 0; r < 16; ++r) p0[r] = fmaf(p0[r], C, mnC); for (int r = 0; r < 16; ++r) p1[r] = fmaf(p1[r], C, mnC);
;   for (int r = 0; r < 16; ++r) p0[r] = __builtin_amdgcn_exp2f(p0[r]);
; }
; __device__ __forceinline__ void finishSM(f32x16& p0, f32x16& p1, float alpha, float& l_reg, i32x8& pa) {
;   for (int r = 0; r < 16; ++r) p1[r] = __builtin_amdgcn_exp2f(p1[r]);
;   float ps = 0; for (int r = 0; r < 16; ++r) ps += p0[r]; for (int r = 0; r < 16; ++r) ps += p1[r];
;   { auto rr = __builtin_amdgcn_permlane32_swap(__float_as_uint(ps), __float_as_uint(ps), false, false);
;     ps = __uint_as_float(rr[0]) + __uint_as_float(rr[1]); }
;   l_reg = l_reg * alpha + ps;
; #pragma unroll
;   for (int i = 0; i < 4; ++i) { int w0 = 0, w1 = 0;
;     w0 = __builtin_amdgcn_cvt_pk_fp8_f32(p0[4 * i], p0[4 * i + 1], w0, false); w0 = __builtin_amdgcn_cvt_pk_fp8_f32(p0[4 * i + 2], p0[4 * i + 3], w0, true);
;     w1 = __builtin_amdgcn_cvt_pk_fp8_f32(p1[4 * i], p1[4 * i + 1], w1, false); w1 = __builtin_amdgcn_cvt_pk_fp8_f32(p1[4 * i + 2], p1[4 * i + 3], w1, true);
;     pa[i] = w0; pa[4 + i] = w1; }
; }
; __device__ __forceinline__ void attn_body(const unsigned char* __restrict__ Qb, const unsigned char* __restrict__ Kh, const unsigned char* __restrict__ Vt,
;                                           bf16_t* __restrict__ Ob, int seq, char* lds) {
;     ...
;   for (int j = 1; j + 1 < NT; j += 2) {
;     STEP(j, pB0, pB1, mnB, alB, pA0, pA1, alA);
;     STEP(j + 1, pA0, pA1, mnA, alA, pB0, pB1, alB);
;   }
.Latt_m_done_3_r1:
	s_nop 3
	s_waitcnt lgkmcnt(0)
	s_barrier
	v_max3_f32 v228, v64, v65, v66
	v_max3_f32 v229, v80, v81, v82
	v_max3_f32 v228, v228, v67, v68
	v_max3_f32 v229, v229, v83, v84
	v_max3_f32 v228, v228, v69, v70
	v_max3_f32 v229, v229, v85, v86
	v_max3_f32 v228, v228, v71, v72
	v_max3_f32 v229, v229, v87, v88
	v_max3_f32 v228, v228, v73, v74
	v_max3_f32 v229, v229, v89, v90
	v_max3_f32 v228, v228, v75, v76
	v_max3_f32 v229, v229, v91, v92
	v_max3_f32 v228, v228, v77, v78
	v_max3_f32 v229, v229, v93, v94
	v_max3_f32 v228, v228, v79, v95
	v_max_f32_e32 v228, v228, v229
	s_mov_b32 s5, 7
	v_cmp_ge_f32_e32 vcc, s13, v228
	v_mov_b32_e32 v226, 1.0
	s_cmp_eq_u64 vcc, exec
	s_cbranch_scc0 .Latt_rare
.Latt_rare_back_7:
	v_exp_f32_e32 v64, v64
	v_exp_f32_e32 v65, v65
	v_exp_f32_e32 v66, v66
	v_exp_f32_e32 v67, v67
	v_add_f32_e32 v230, v64, v65
	v_exp_f32_e32 v68, v68
	v_add_f32_e32 v230, v66, v230
	v_exp_f32_e32 v69, v69
	v_cvt_pk_fp8_f32 v120, v64, v65
	v_add_f32_e32 v230, v67, v230
	v_exp_f32_e32 v70, v70
	v_add_f32_e32 v230, v68, v230
	v_exp_f32_e32 v71, v71
	v_cvt_pk_fp8_f32 v120, v66, v67 op_sel:[0,0,1]
	v_add_f32_e32 v230, v69, v230
	v_exp_f32_e32 v72, v72
	v_add_f32_e32 v230, v70, v230
	v_exp_f32_e32 v73, v73
	v_cvt_pk_fp8_f32 v121, v68, v69
	v_add_f32_e32 v230, v71, v230
	v_exp_f32_e32 v74, v74
	v_add_f32_e32 v230, v72, v230
	v_exp_f32_e32 v75, v75
	v_cvt_pk_fp8_f32 v121, v70, v71 op_sel:[0,0,1]
	v_add_f32_e32 v230, v73, v230
	v_exp_f32_e32 v76, v76
	v_add_f32_e32 v230, v74, v230
	v_exp_f32_e32 v77, v77
	v_cvt_pk_fp8_f32 v122, v72, v73
	v_add_f32_e32 v230, v75, v230
	v_exp_f32_e32 v78, v78
	v_add_f32_e32 v230, v76, v230
	v_exp_f32_e32 v79, v79
	v_cvt_pk_fp8_f32 v122, v74, v75 op_sel:[0,0,1]
	v_add_f32_e32 v230, v77, v230
	v_exp_f32_e32 v80, v80
	v_add_f32_e32 v230, v78, v230
	v_exp_f32_e32 v81, v81
	v_cvt_pk_fp8_f32 v123, v76, v77
	v_add_f32_e32 v230, v79, v230
	v_exp_f32_e32 v82, v82
	v_add_f32_e32 v230, v80, v230
	v_exp_f32_e32 v83, v83
	v_cvt_pk_fp8_f32 v123, v78, v79 op_sel:[0,0,1]
	v_add_f32_e32 v230, v81, v230
	v_exp_f32_e32 v84, v84
	v_add_f32_e32 v230, v82, v230
	v_exp_f32_e32 v85, v85
	v_cvt_pk_fp8_f32 v124, v80, v81
	v_add_f32_e32 v230, v83, v230
	v_exp_f32_e32 v86, v86
	v_add_f32_e32 v230, v84, v230
	v_exp_f32_e32 v87, v87
	v_cvt_pk_fp8_f32 v124, v82, v83 op_sel:[0,0,1]
	v_add_f32_e32 v230, v85, v230
	v_exp_f32_e32 v88, v88
	v_add_f32_e32 v230, v86, v230
	v_exp_f32_e32 v89, v89
	v_cvt_pk_fp8_f32 v125, v84, v85
	v_add_f32_e32 v230, v87, v230
	v_exp_f32_e32 v90, v90
	v_add_f32_e32 v230, v88, v230
	v_exp_f32_e32 v91, v91
	v_cvt_pk_fp8_f32 v125, v86, v87 op_sel:[0,0,1]
	v_add_f32_e32 v230, v89, v230
	v_exp_f32_e32 v92, v92
	v_add_f32_e32 v230, v90, v230
	v_exp_f32_e32 v93, v93
	v_cvt_pk_fp8_f32 v126, v88, v89
	v_add_f32_e32 v230, v91, v230
	v_exp_f32_e32 v94, v94
	v_add_f32_e32 v230, v92, v230
	v_exp_f32_e32 v95, v95
	v_cvt_pk_fp8_f32 v126, v90, v91 op_sel:[0,0,1]
	v_add_f32_e32 v230, v93, v230
	v_add_f32_e32 v230, v94, v230
	v_cvt_pk_fp8_f32 v127, v92, v93
	v_add_f32_e32 v230, v95, v230
	v_cvt_pk_fp8_f32 v127, v94, v95 op_sel:[0,0,1]
	v_fma_f32 v194, v194, v226, v230
	s_waitcnt lgkmcnt(0)
	s_add_u32 s6, s6, 1
	s_cmp_lt_u32 s6, 128
	s_cbranch_scc1 .Latt_loop_r1

; __device__ __forceinline__ void partialSM(f32x16& p0, f32x16& p1, float& m_reg, float& mn, float& alpha) {
;     ...
;   { auto rr = __builtin_amdgcn_permlane32_swap(__float_as_uint(pmax), __float_as_uint(pmax), false, false);
;     pmax = fmaxf(__uint_as_float(rr[0]), __uint_as_float(rr[1])); }
;   if (__builtin_expect(__all(pmax - m_reg <= THR / SCALE), 1)) { mn = m_reg; alpha = 1.f; }
;   else { mn = fmaxf(m_reg, pmax); alpha = __builtin_amdgcn_exp2f((m_reg - mn) * C); m_reg = mn; }
;   float mnC = -mn * C + 5.f;
;   for (int r = 0; r < 16; ++r) p0[r] = fmaf(p0[r], C, mnC); for (int r = 0; r < 16; ++r) p1[r] = fmaf(p1[r], C, mnC);
.Latt_rare:
	v_mov_b32_e32 v229, v228
	s_nop 1
	v_permlane32_swap_b32_e32 v228, v229
	v_max_f32_e32 v228, v228, v229
	v_sub_f32_e32 v229, v228, v227
	v_max_f32_e32 v229, v193, v229
	v_sub_f32_e32 v231, v193, v229
	v_exp_f32_e32 v226, v231
	v_mov_b32_e32 v193, v229
	v_sub_f32_e32 v231, v236, v229
	v_sub_f32_e32 v229, v231, v227
	v_mov_b32_e32 v227, v231
	v_add_f32_e32 v64, v64, v229
	v_add_f32_e32 v65, v65, v229
	v_add_f32_e32 v66, v66, v229
	v_add_f32_e32 v67, v67, v229
	v_add_f32_e32 v68, v68, v229
	v_add_f32_e32 v69, v69, v229
	v_add_f32_e32 v70, v70, v229
	v_add_f32_e32 v71, v71, v229
	v_add_f32_e32 v72, v72, v229
	v_add_f32_e32 v73, v73, v229
	v_add_f32_e32 v74, v74, v229
	v_add_f32_e32 v75, v75, v229
	v_add_f32_e32 v76, v76, v229
	v_add_f32_e32 v77, v77, v229
	v_add_f32_e32 v78, v78, v229
	v_add_f32_e32 v79, v79, v229
	v_add_f32_e32 v80, v80, v229
	v_add_f32_e32 v81, v81, v229
	v_add_f32_e32 v82, v82, v229
	v_add_f32_e32 v83, v83, v229
	v_add_f32_e32 v84, v84, v229
	v_add_f32_e32 v85, v85, v229
	v_add_f32_e32 v86, v86, v229
	v_add_f32_e32 v87, v87, v229
	v_add_f32_e32 v88, v88, v229
	v_add_f32_e32 v89, v89, v229
	v_add_f32_e32 v90, v90, v229
	v_add_f32_e32 v91, v91, v229
	v_add_f32_e32 v92, v92, v229
	v_add_f32_e32 v93, v93, v229
	v_add_f32_e32 v94, v94, v229
	v_add_f32_e32 v95, v95, v229
	v_mov_b32_e32 v160, v227
	v_mov_b32_e32 v161, v227
	v_mov_b32_e32 v162, v227
	v_mov_b32_e32 v163, v227
	v_mov_b32_e32 v164, v227
	v_mov_b32_e32 v165, v227
	v_mov_b32_e32 v166, v227
	v_mov_b32_e32 v167, v227
	v_mov_b32_e32 v168, v227
	v_mov_b32_e32 v169, v227
	v_mov_b32_e32 v170, v227
	v_mov_b32_e32 v171, v227
	v_mov_b32_e32 v172, v227
	v_mov_b32_e32 v173, v227
	v_mov_b32_e32 v174, v227
	v_mov_b32_e32 v175, v227
	s_mov_b32 exec_hi, 0
	ds_write_b32 v222, v226 offset:128
	s_mov_b64 exec, -1
	s_waitcnt lgkmcnt(0)
	ds_read_b128 v[176:179], v223 offset:128
	ds_read_b128 v[180:183], v223 offset:160
	ds_read_b128 v[184:187], v223 offset:192
	ds_read_b128 v[188:191], v223 offset:224
	s_waitcnt lgkmcnt(0)
	v_mul_f32_e32 v0, v0, v176
	v_mul_f32_e32 v1, v1, v177
	v_mul_f32_e32 v2, v2, v178
	v_mul_f32_e32 v3, v3, v179
	v_mul_f32_e32 v4, v4, v180
	v_mul_f32_e32 v5, v5, v181
	v_mul_f32_e32 v6, v6, v182
	v_mul_f32_e32 v7, v7, v183
	v_mul_f32_e32 v8, v8, v184
	v_mul_f32_e32 v9, v9, v185
	v_mul_f32_e32 v10, v10, v186
	v_mul_f32_e32 v11, v11, v187
	v_mul_f32_e32 v12, v12, v188
	v_mul_f32_e32 v13, v13, v189
	v_mul_f32_e32 v14, v14, v190
	v_mul_f32_e32 v15, v15, v191
	v_mul_f32_e32 v16, v16, v176
	v_mul_f32_e32 v17, v17, v177
	v_mul_f32_e32 v18, v18, v178
	v_mul_f32_e32 v19, v19, v179
	v_mul_f32_e32 v20, v20, v180
	v_mul_f32_e32 v21, v21, v181
	v_mul_f32_e32 v22, v22, v182
	v_mul_f32_e32 v23, v23, v183
	v_mul_f32_e32 v24, v24, v184
	v_mul_f32_e32 v25, v25, v185
	v_mul_f32_e32 v26, v26, v186
	v_mul_f32_e32 v27, v27, v187
	v_mul_f32_e32 v28, v28, v188
	v_mul_f32_e32 v29, v29, v189
	v_mul_f32_e32 v30, v30, v190
	v_mul_f32_e32 v31, v31, v191
	v_mul_f32_e32 v32, v32, v176
	v_mul_f32_e32 v33, v33, v177
	v_mul_f32_e32 v34, v34, v178
	v_mul_f32_e32 v35, v35, v179
	v_mul_f32_e32 v36, v36, v180
	v_mul_f32_e32 v37, v37, v181
	v_mul_f32_e32 v38, v38, v182
	v_mul_f32_e32 v39, v39, v183
	v_mul_f32_e32 v40, v40, v184
	v_mul_f32_e32 v41, v41, v185
	v_mul_f32_e32 v42, v42, v186
	v_mul_f32_e32 v43, v43, v187
	v_mul_f32_e32 v44, v44, v188
	v_mul_f32_e32 v45, v45, v189
	v_mul_f32_e32 v46, v46, v190
	v_mul_f32_e32 v47, v47, v191
	v_mul_f32_e32 v48, v48, v176
	v_mul_f32_e32 v49, v49, v177
	v_mul_f32_e32 v50, v50, v178
	v_mul_f32_e32 v51, v51, v179
	v_mul_f32_e32 v52, v52, v180
	v_mul_f32_e32 v53, v53, v181
	v_mul_f32_e32 v54, v54, v182
	v_mul_f32_e32 v55, v55, v183
	v_mul_f32_e32 v56, v56, v184
	v_mul_f32_e32 v57, v57, v185
	v_mul_f32_e32 v58, v58, v186
	v_mul_f32_e32 v59, v59, v187
	v_mul_f32_e32 v60, v60, v188
	v_mul_f32_e32 v61, v61, v189
	v_mul_f32_e32 v62, v62, v190
	v_mul_f32_e32 v63, v63, v191
	s_cmp_eq_u32 s5, 0
	s_cbranch_scc1 .Latt_rare_back_0
	s_cmp_eq_u32 s5, 1
	s_cbranch_scc1 .Latt_rare_back_1
	s_cmp_eq_u32 s5, 2
	s_cbranch_scc1 .Latt_rare_back_2
	s_cmp_eq_u32 s5, 3
	s_cbranch_scc1 .Latt_rare_back_3
	s_cmp_eq_u32 s5, 4
	s_cbranch_scc1 .Latt_rare_back_4
	s_cmp_eq_u32 s5, 5
	s_cbranch_scc1 .Latt_rare_back_5
	s_cmp_eq_u32 s5, 6
	s_cbranch_scc1 .Latt_rare_back_6
	s_branch .Latt_rare_back_7
